# k31: k30 + first grid barrier also on the short protocol (after its set-up part)
# baseline (speedup 1.0000x reference)
; __device__ __forceinline__ unsigned xb_ld(unsigned* p)              { return __hip_atomic_load(p, __ATOMIC_RELAXED, __HIP_MEMORY_SCOPE_AGENT); }
; __device__ __forceinline__ unsigned xb_add(unsigned* p, unsigned v) { return __hip_atomic_fetch_add(p, v, __ATOMIC_RELAXED, __HIP_MEMORY_SCOPE_AGENT); }
; #define XB_SPIN(cond, bar) do { unsigned _sp = 0; while (cond) { __builtin_amdgcn_s_sleep(1); \
;     if ((++_sp & 255u) == 0u) { if (xb_ld(&(bar)[XB_TMO])) break; if (_sp > XB_SPIN_CAP) { atomicAdd(&(bar)[XB_TMO], 1u); break; } } } } while (0)
; __device__ __forceinline__ void xcd_barrier(const XcdBarrier& b) {
;     asm volatile("s_waitcnt vmcnt(0)" ::: "memory");
;     __syncthreads();
;     if (threadIdx.x == 0) {
;         unsigned* bar = b.bar;
;         __builtin_amdgcn_s_waitcnt(0);
;         unsigned nloc = b.st[0], nx = b.st[1];
;         if (nloc == 0u) { xcd_barrier_complete(bar, b.x, nloc, nx); b.st[0] = nloc; b.st[1] = nx; }
;         const unsigned old = xb_add(&bar[XB_XSUB(b.x)], 1u);
;         const unsigned gen = old / nloc;
;         if (old + 1u == (gen + 1u) * nloc) {
;             __builtin_amdgcn_fence(__ATOMIC_RELEASE, "agent");
;             asm volatile("s_waitcnt vmcnt(0)" ::: "memory");
;             const unsigned og = xb_add(&bar[XB_TOP], 1u);
;             const unsigned tg = og / nx;
;             if (og + 1u == (tg + 1u) * nx) xb_add(&bar[XB_TOPGEN], 1u);
;             else XB_SPIN(xb_ld(&bar[XB_TOPGEN]) == tg, bar);
;             __builtin_amdgcn_fence(__ATOMIC_ACQUIRE, "agent");
;             xb_add(&bar[XB_XGEN(b.x)], 1u);
;             asm volatile("s_waitcnt vmcnt(0)" ::: "memory");
;         } else {
;             XB_SPIN(xb_ld(&bar[XB_XGEN(b.x)]) == gen, bar);
;             __builtin_amdgcn_fence(__ATOMIC_ACQUIRE, "agent");
;             asm volatile("s_waitcnt vmcnt(0)" ::: "memory");
;         }
;     }
;     __syncthreads();
; }
.LBB0_104:
	s_add_i32 s8, 0, 0x20160
	v_mov_b32_e32 v0, s8
	ds_read_b32 v2, v0
	ds_read_b32 v3, v0 offset:4
	v_readlane_b32 s9, v255, 3
	v_mov_b32_e32 v1, 1
	s_lshl_b32 s9, s9, 8
	s_add_i32 s9, s9, 0x8000
	v_mov_b32_e32 v0, s9
	s_waitcnt vmcnt(0) lgkmcnt(0)
	global_atomic_add v4, v0, v1, s[92:93] sc0
	v_readfirstlane_b32 s10, v2
	v_readfirstlane_b32 s11, v3
	s_nop 3
	s_mul_i32 s10, s10, 1
	s_mul_i32 s11, s11, 1
	s_waitcnt vmcnt(0)
	v_readfirstlane_b32 s12, v4
	s_nop 3
	s_add_i32 s12, s12, 1
	s_cmp_lg_u32 s12, s10
	s_cbranch_scc1 .Lmy_gb1_wait
	buffer_wbl2 sc1
	s_waitcnt vmcnt(0) lgkmcnt(0)
	v_mov_b32_e32 v0, 0x9000
	global_atomic_add v0, v1, s[92:93]

; #define LAS __attribute__((address_space(3)))
; __device__ __forceinline__ unsigned xb_ld(unsigned* p)              { return __hip_atomic_load(p, __ATOMIC_RELAXED, __HIP_MEMORY_SCOPE_AGENT); }
; __device__ __forceinline__ unsigned xb_add(unsigned* p, unsigned v) { return __hip_atomic_fetch_add(p, v, __ATOMIC_RELAXED, __HIP_MEMORY_SCOPE_AGENT); }
; __device__ __forceinline__ void xcd_barrier(const XcdBarrier& b) {
;     asm volatile("s_waitcnt vmcnt(0)" ::: "memory");
;     __syncthreads();
;     if (threadIdx.x == 0) {
;         unsigned* bar = b.bar;
;         __builtin_amdgcn_s_waitcnt(0);
;         unsigned nloc = b.st[0], nx = b.st[1];
;         if (nloc == 0u) { xcd_barrier_complete(bar, b.x, nloc, nx); b.st[0] = nloc; b.st[1] = nx; }
;         const unsigned old = xb_add(&bar[XB_XSUB(b.x)], 1u);
;         const unsigned gen = old / nloc;
;         if (old + 1u == (gen + 1u) * nloc) {
;             __builtin_amdgcn_fence(__ATOMIC_RELEASE, "agent");
;             asm volatile("s_waitcnt vmcnt(0)" ::: "memory");
;             const unsigned og = xb_add(&bar[XB_TOP], 1u);
;             const unsigned tg = og / nx;
;             if (og + 1u == (tg + 1u) * nx) xb_add(&bar[XB_TOPGEN], 1u);
;             else XB_SPIN(xb_ld(&bar[XB_TOPGEN]) == tg, bar);
;             __builtin_amdgcn_fence(__ATOMIC_ACQUIRE, "agent");
;             xb_add(&bar[XB_XGEN(b.x)], 1u);
;             asm volatile("s_waitcnt vmcnt(0)" ::: "memory");
;         } else {
;             XB_SPIN(xb_ld(&bar[XB_XGEN(b.x)]) == gen, bar);
;             __builtin_amdgcn_fence(__ATOMIC_ACQUIRE, "agent");
;             asm volatile("s_waitcnt vmcnt(0)" ::: "memory");
;         }
;     }
;     __syncthreads();
; }
; __global__ void __launch_bounds__(NTHR, 2) hymba_fwd(Params P) {
;     ...
;         __syncthreads();
;         LAS float* w8 = (LAS float*)lds;
; #pragma unroll
;         for (int i0 = 0; i0 < 8192; i0 += NTHR) { const int i = i0 + tid, c = i >> 10, k = i & 1023; w8[i] = P.w_in[(size_t)k * INW + NPROJ + c]; }
;         __syncthreads();
;         const int gw = blk * NWAVES + wave, NGW = G * NWAVES;
;         constexpr int NPAIR = MT / 2; const int per = (NPAIR + NGW - 1) / NGW;
;         const int p_lo = gw * per, p_hi = (p_lo + per < NPAIR) ? p_lo + per : NPAIR;
.Lmy_gb1_done:
	buffer_inv sc1
	s_waitcnt vmcnt(0)
.LBB0_140:
	s_or_b64 exec, exec, s[0:1]
	v_mov_b32_e32 v2, v208
	s_waitcnt lgkmcnt(0)
	s_barrier
	v_mov_b32_e32 v1, 0
	v_and_b32_e32 v0, 0x3ff, v2
	v_mul_u32_u24_e32 v0, 0xc08, v0
	v_lshlrev_b32_e32 v0, 2, v0
	v_lshl_add_u64 v[6:7], s[60:61], 0, v[0:1]
	v_add_u32_e32 v0, 0x200, v2
	v_ashrrev_i32_e32 v8, 10, v0
	v_and_b32_e32 v0, 0x3ff, v0
	v_mul_u32_u24_e32 v0, 0xc08, v0
	v_lshlrev_b32_e32 v0, 2, v0
	v_ashrrev_i32_e32 v9, 31, v8
	v_lshl_add_u64 v[10:11], s[60:61], 0, v[0:1]
	v_add_u32_e32 v0, 0x400, v2
	v_lshl_add_u64 v[8:9], v[8:9], 2, v[10:11]
	v_ashrrev_i32_e32 v10, 10, v0
	v_add_u32_e32 v0, 0x600, v2
	v_ashrrev_i32_e32 v12, 10, v0
	v_and_b32_e32 v0, 0x3ff, v0
	v_mul_u32_u24_e32 v0, 0xc08, v0
	v_lshlrev_b32_e32 v0, 2, v0
	v_ashrrev_i32_e32 v13, 31, v12
	v_lshl_add_u64 v[14:15], s[60:61], 0, v[0:1]
	v_add_u32_e32 v0, 0x800, v2
	v_lshl_add_u64 v[12:13], v[12:13], 2, v[14:15]
	v_ashrrev_i32_e32 v14, 10, v0
	v_add_u32_e32 v0, 0xa00, v2
	v_ashrrev_i32_e32 v16, 10, v0
	v_and_b32_e32 v0, 0x3ff, v0
	v_mul_u32_u24_e32 v0, 0xc08, v0
	s_mov_b64 s[0:1], 0x3000
	v_lshlrev_b32_e32 v0, 2, v0
	v_lshl_add_u64 v[6:7], v[6:7], 0, s[0:1]
	s_movk_i32 s0, 0x3000
	v_ashrrev_i32_e32 v17, 31, v16
	v_lshl_add_u64 v[18:19], s[60:61], 0, v[0:1]
	v_add_u32_e32 v0, 0xc00, v2
	v_add_co_u32_e32 v8, vcc, s0, v8
	v_lshl_add_u64 v[16:17], v[16:17], 2, v[18:19]
	v_ashrrev_i32_e32 v18, 10, v0
	v_add_u32_e32 v0, 0xe00, v2
	v_addc_co_u32_e32 v9, vcc, 0, v9, vcc
	v_ashrrev_i32_e32 v20, 10, v0
	v_and_b32_e32 v0, 0x3ff, v0
	v_add_co_u32_e32 v12, vcc, s0, v12
	v_mul_u32_u24_e32 v0, 0xc08, v0
	s_nop 0
	v_addc_co_u32_e32 v13, vcc, 0, v13, vcc
	v_lshlrev_b32_e32 v0, 2, v0
	v_ashrrev_i32_e32 v4, 10, v2
	v_add_co_u32_e32 v16, vcc, s0, v16
	v_ashrrev_i32_e32 v21, 31, v20
	v_lshl_add_u64 v[22:23], s[60:61], 0, v[0:1]
	v_ashrrev_i32_e32 v5, 31, v4
	v_addc_co_u32_e32 v17, vcc, 0, v17, vcc
	v_lshl_add_u64 v[20:21], v[20:21], 2, v[22:23]
	v_lshl_add_u64 v[4:5], v[4:5], 2, v[6:7]
	v_ashrrev_i32_e32 v11, 31, v10
	v_ashrrev_i32_e32 v15, 31, v14
	v_ashrrev_i32_e32 v19, 31, v18
	v_add_co_u32_e32 v20, vcc, s0, v20
	v_add_u32_e32 v0, 0x1000, v2
	s_barrier
	v_lshl_add_u64 v[10:11], v[10:11], 2, v[6:7]
	v_lshl_add_u64 v[14:15], v[14:15], 2, v[6:7]
	v_lshl_add_u64 v[18:19], v[18:19], 2, v[6:7]
	v_addc_co_u32_e32 v21, vcc, 0, v21, vcc
	global_load_dword v3, v[4:5], off
	global_load_dword v22, v[8:9], off
	global_load_dword v23, v[10:11], off
	global_load_dword v24, v[12:13], off
	global_load_dword v25, v[14:15], off
	global_load_dword v26, v[16:17], off
	global_load_dword v27, v[18:19], off
	global_load_dword v28, v[20:21], off
	v_ashrrev_i32_e32 v4, 10, v0
	v_add_u32_e32 v0, 0x1200, v2
	v_ashrrev_i32_e32 v8, 10, v0
	v_and_b32_e32 v0, 0x3ff, v0
	v_mul_u32_u24_e32 v0, 0xc08, v0
	v_lshlrev_b32_e32 v0, 2, v0
	v_ashrrev_i32_e32 v9, 31, v8
	v_lshl_add_u64 v[10:11], s[60:61], 0, v[0:1]
	v_add_u32_e32 v0, 0x1400, v2
	v_lshl_add_u64 v[8:9], v[8:9], 2, v[10:11]
	v_ashrrev_i32_e32 v10, 10, v0
	v_add_u32_e32 v0, 0x1600, v2
	v_ashrrev_i32_e32 v12, 10, v0
	v_and_b32_e32 v0, 0x3ff, v0
	v_mul_u32_u24_e32 v0, 0xc08, v0
	v_lshlrev_b32_e32 v0, 2, v0
	v_ashrrev_i32_e32 v13, 31, v12
	v_lshl_add_u64 v[14:15], s[60:61], 0, v[0:1]
	v_add_u32_e32 v0, 0x1800, v2
	v_lshl_add_u64 v[12:13], v[12:13], 2, v[14:15]
	v_ashrrev_i32_e32 v14, 10, v0
	v_add_u32_e32 v0, 0x1a00, v2
	v_ashrrev_i32_e32 v16, 10, v0
	v_and_b32_e32 v0, 0x3ff, v0
	v_mul_u32_u24_e32 v0, 0xc08, v0
	v_lshlrev_b32_e32 v0, 2, v0
	v_ashrrev_i32_e32 v17, 31, v16
	v_lshl_add_u64 v[18:19], s[60:61], 0, v[0:1]
	v_add_u32_e32 v0, 0x1c00, v2
	v_lshl_add_u64 v[16:17], v[16:17], 2, v[18:19]
	v_ashrrev_i32_e32 v18, 10, v0
	v_ashrrev_i32_e32 v5, 31, v4
	v_add_co_u32_e32 v8, vcc, s0, v8
	v_ashrrev_i32_e32 v11, 31, v10
	v_ashrrev_i32_e32 v15, 31, v14
	v_ashrrev_i32_e32 v19, 31, v18
	v_add_u32_e32 v0, 0x1e00, v2
	v_lshl_add_u64 v[4:5], v[4:5], 2, v[6:7]
	v_addc_co_u32_e32 v9, vcc, 0, v9, vcc
	v_lshl_add_u64 v[10:11], v[10:11], 2, v[6:7]
	v_lshl_add_u64 v[14:15], v[14:15], 2, v[6:7]
	v_lshl_add_u64 v[6:7], v[18:19], 2, v[6:7]
	v_ashrrev_i32_e32 v18, 10, v0
	v_and_b32_e32 v0, 0x3ff, v0
	v_add_co_u32_e32 v12, vcc, s0, v12
	v_mul_u32_u24_e32 v0, 0xc08, v0
	s_nop 0
	v_addc_co_u32_e32 v13, vcc, 0, v13, vcc
	v_lshlrev_b32_e32 v0, 2, v0
	v_add_co_u32_e32 v16, vcc, s0, v16
	v_ashrrev_i32_e32 v19, 31, v18
	v_lshl_add_u64 v[20:21], s[60:61], 0, v[0:1]
	v_addc_co_u32_e32 v17, vcc, 0, v17, vcc
	v_lshl_add_u64 v[18:19], v[18:19], 2, v[20:21]
	v_add_co_u32_e32 v18, vcc, s0, v18
	s_lshl_b32 s0, s94, 3
	s_nop 0
	v_addc_co_u32_e32 v19, vcc, 0, v19, vcc
	global_load_dword v0, v[4:5], off
	s_nop 0
	global_load_dword v4, v[8:9], off
	global_load_dword v5, v[10:11], off
	s_nop 0
	global_load_dword v8, v[12:13], off
	global_load_dword v9, v[14:15], off
	global_load_dword v10, v[16:17], off
	s_nop 0
	global_load_dword v6, v[6:7], off
	s_nop 0
	global_load_dword v7, v[18:19], off
	s_add_u32 s40, s92, 0x1800000
	s_addc_u32 s41, s93, 0
	v_lshl_add_u32 v11, v2, 2, 0
	s_abs_i32 s5, s0
	s_waitcnt vmcnt(14)
	ds_write2st64_b32 v11, v3, v22 offset1:8
	s_waitcnt vmcnt(12)
	ds_write2st64_b32 v11, v23, v24 offset0:16 offset1:24
	s_waitcnt vmcnt(10)
	ds_write2st64_b32 v11, v25, v26 offset0:32 offset1:40
	s_waitcnt vmcnt(8)
	ds_write2st64_b32 v11, v27, v28 offset0:48 offset1:56
	s_waitcnt vmcnt(6)
	ds_write2st64_b32 v11, v0, v4 offset0:64 offset1:72
	s_waitcnt vmcnt(4)
	ds_write2st64_b32 v11, v5, v8 offset0:80 offset1:88
	s_waitcnt vmcnt(2)
	ds_write2st64_b32 v11, v9, v10 offset0:96 offset1:104
	s_waitcnt vmcnt(0)
	ds_write2st64_b32 v11, v6, v7 offset0:112 offset1:120
	v_cvt_f32_u32_e32 v0, s5
	v_readfirstlane_b32 s1, v2
	s_lshl_b32 s3, s2, 3
	s_add_i32 s4, s0, 0x80ff
	v_rcp_iflag_f32_e32 v0, v0
	s_ashr_i32 s1, s1, 6
	s_add_i32 s1, s1, s3
	s_xor_b32 s0, s4, s0
	v_mul_f32_e32 v0, 0x4f7ffffe, v0
	v_cvt_u32_f32_e32 v0, v0
	s_abs_i32 s3, s4
	s_sub_i32 s4, 0, s5
	s_ashr_i32 s0, s0, 31
	v_readfirstlane_b32 s6, v0
	s_mul_i32 s4, s4, s6
	s_mul_hi_u32 s4, s6, s4
	s_add_i32 s6, s6, s4
	s_mul_hi_u32 s4, s3, s6
	s_mul_i32 s6, s4, s5
	s_sub_i32 s3, s3, s6
	s_add_i32 s6, s4, 1
	s_sub_i32 s7, s3, s5
	s_cmp_ge_u32 s3, s5
	s_cselect_b32 s4, s6, s4
	s_cselect_b32 s3, s7, s3
	s_add_i32 s6, s4, 1
	s_cmp_ge_u32 s3, s5
	s_cselect_b32 s3, s6, s4
	s_xor_b32 s3, s3, s0
	s_sub_i32 s0, s3, s0
	s_mul_i32 s50, s0, s1
	s_add_i32 s0, s50, s0
	s_min_i32 s3, s0, 0x8100
	s_cmp_lt_i32 s50, s3
	v_mbcnt_lo_u32_b32 v202, -1, 0
	s_waitcnt lgkmcnt(0)
	s_barrier
; __global__ void __launch_bounds__(NTHR, 2) hymba_fwd(Params P) {
;     ...
;         int cur_b = -1; f32x4 Ak[4], Bk[4]; float bsel = 0.f;
;         for (int j = 0; j < 4; ++j) { Ak[j] = (f32x4){0.f, 0.f, 0.f, 0.f}; Bk[j] = Ak[j]; }
;         f32x4 x0[4], x1[4];
;         auto rowptr = [&](int m) -> const float* { return (m < PT) ? P.x_prompt + (size_t)m * DM : P.x_sample + (size_t)(m - PT) * DM; };
;         if (p_lo < p_hi) { const float* r0 = rowptr(2 * p_lo); const float* r1 = rowptr(2 * p_lo + 1);
; #pragma unroll
;             for (int j = 0; j < 4; ++j) { x0[j] = __builtin_nontemporal_load((const f32x4*)r0 + lane + 64 * j); x1[j] = __builtin_nontemporal_load((const f32x4*)r1 + lane + 64 * j); } }
	s_cbranch_scc0 .LBB0_150
	s_lshl_b32 s44, s50, 1
	s_add_i32 s0, s44, 0xffff0000
	s_ashr_i32 s1, s44, 31
	s_cmp_lt_i32 s50, 0x8000
	s_cselect_b32 s1, s1, 0
	s_cselect_b32 s0, s44, s0
	s_cselect_b32 s4, s37, s39
	s_cselect_b32 s5, s36, s38
	s_lshl_b64 s[0:1], s[0:1], 12
	s_add_u32 s0, s5, s0
	s_addc_u32 s1, s4, s1
	s_or_b32 s4, s44, 1
	s_add_i32 s6, s44, 0xffff0001
	s_ashr_i32 s5, s4, 31
	s_cmp_lt_i32 s4, 0x10000
	s_cselect_b32 s5, s5, 0
	s_cselect_b32 s4, s4, s6
	v_and_b32_e32 v4, 63, v2
	s_cselect_b32 s6, s37, s39
	s_cselect_b32 s7, s36, s38
	s_lshl_b64 s[4:5], s[4:5], 12
	s_add_u32 s4, s7, s4
	v_lshlrev_b32_e32 v100, 4, v4
	s_addc_u32 s5, s6, s5
	global_load_dwordx4 v[96:99], v100, s[0:1] nt
	global_load_dwordx4 v[88:91], v100, s[0:1] offset:1024 nt
	global_load_dwordx4 v[92:95], v100, s[4:5] nt
	global_load_dwordx4 v[84:87], v100, s[4:5] offset:1024 nt
	global_load_dwordx4 v[48:51], v100, s[0:1] offset:2048 nt
	global_load_dwordx4 v[40:43], v100, s[0:1] offset:3072 nt
	global_load_dwordx4 v[44:47], v100, s[4:5] offset:2048 nt
	global_load_dwordx4 v[36:39], v100, s[4:5] offset:3072 nt
	v_and_b32_e32 v3, 32, v2
	v_cmp_eq_u32_e64 s[0:1], 0, v3
	v_and_b32_e32 v3, 16, v2
	v_cmp_eq_u32_e64 s[4:5], 0, v3
	v_and_b32_e32 v3, 8, v2
	v_cmp_eq_u32_e64 s[6:7], 0, v3
	v_and_b32_e32 v3, 4, v2
	v_lshlrev_b32_e32 v6, 2, v4
	v_bfe_u32 v102, v2, 2, 3
	v_cmp_eq_u32_e64 s[8:9], 0, v3
	v_lshlrev_b32_e32 v8, 3, v4
	v_mov_b32_e32 v9, v1
	v_and_b32_e32 v3, 3, v2
	v_lshlrev_b32_e32 v0, 2, v102
	v_lshl_add_u64 v[106:107], s[40:41], 0, v[8:9]
	v_cmp_eq_u32_e64 s[10:11], 0, v3
	v_bfe_u32 v103, v2, 5, 1
	v_cmp_gt_u32_e64 s[12:13], 32, v4
	v_mov_b32_e32 v101, v1
	v_or_b32_e32 v8, 0x100, v6
	v_or_b32_e32 v10, 0x200, v6
	v_or_b32_e32 v12, 0x300, v6
	v_mov_b32_e32 v2, v1
	v_mov_b32_e32 v3, v1
	v_lshlrev_b32_e32 v130, 4, v4
	v_lshl_add_u64 v[104:105], s[62:63], 0, v[0:1]
	v_lshl_add_u64 v[108:109], s[42:43], 0, v[0:1]
	v_lshl_add_u64 v[110:111], s[58:59], 0, v[100:101]
	v_mov_b32_e32 v0, v1
	v_lshlrev_b32_e32 v101, 2, v6
	v_lshlrev_b32_e32 v113, 2, v8
	v_lshlrev_b32_e32 v128, 2, v10
	v_lshlrev_b32_e32 v129, 2, v12
	v_mov_b64_e32 v[6:7], v[2:3]
	v_mov_b64_e32 v[10:11], v[2:3]
	v_mov_b64_e32 v[14:15], v[2:3]
	v_mov_b64_e32 v[26:27], v[2:3]
	v_mov_b64_e32 v[18:19], v[2:3]
	v_mov_b64_e32 v[22:23], v[2:3]
	v_mov_b64_e32 v[30:31], v[2:3]
	v_mov_b64_e32 v[34:35], v[2:3]
	v_cmp_eq_u32_e64 s[14:15], 1, v102
	v_cmp_eq_u32_e64 s[16:17], 2, v102
	v_cmp_eq_u32_e64 s[18:19], 3, v102
	v_cmp_eq_u32_e64 s[20:21], 4, v102
	v_cmp_eq_u32_e64 s[22:23], 5, v102
	v_cmp_eq_u32_e64 s[24:25], 6, v102
	v_cmp_eq_u32_e64 s[26:27], 7, v102
	s_mov_b32 s51, -1
	v_mbcnt_hi_u32_b32 v131, -1, v202
	s_mov_b32 s33, 0x800000
	v_mov_b32_e32 v132, 0x3ecc95a3
	s_mov_b32 s34, 0xffff
	s_movk_i32 s35, 0x840
	v_mov_b32_e32 v112, 0x358637bd
	v_mov_b32_e32 v133, 0x7f800000
	v_mov_b32_e32 v134, 0x7fc00000
	v_mov_b32_e32 v135, 0xff800000
	v_mov_b64_e32 v[4:5], v[0:1]
	v_mov_b64_e32 v[8:9], v[0:1]
	v_mov_b64_e32 v[12:13], v[0:1]
	v_mov_b64_e32 v[24:25], v[0:1]
	v_mov_b64_e32 v[16:17], v[0:1]
	v_mov_b64_e32 v[20:21], v[0:1]
	v_mov_b64_e32 v[28:29], v[0:1]
	v_mov_b64_e32 v[32:33], v[0:1]
	v_mov_b32_e32 v136, 0
	s_branch .LBB0_143

; __device__ __forceinline__ unsigned xb_ld(unsigned* p)              { return __hip_atomic_load(p, __ATOMIC_RELAXED, __HIP_MEMORY_SCOPE_AGENT); }
; __device__ __forceinline__ unsigned xb_add(unsigned* p, unsigned v) { return __hip_atomic_fetch_add(p, v, __ATOMIC_RELAXED, __HIP_MEMORY_SCOPE_AGENT); }
; #define XB_SPIN(cond, bar) do { unsigned _sp = 0; while (cond) { __builtin_amdgcn_s_sleep(1); \
;     if ((++_sp & 255u) == 0u) { if (xb_ld(&(bar)[XB_TMO])) break; if (_sp > XB_SPIN_CAP) { atomicAdd(&(bar)[XB_TMO], 1u); break; } } } } while (0)
; __device__ __forceinline__ void xcd_barrier(const XcdBarrier& b) {
;     asm volatile("s_waitcnt vmcnt(0)" ::: "memory");
;     __syncthreads();
;     if (threadIdx.x == 0) {
;         unsigned* bar = b.bar;
;         __builtin_amdgcn_s_waitcnt(0);
;         unsigned nloc = b.st[0], nx = b.st[1];
;         if (nloc == 0u) { xcd_barrier_complete(bar, b.x, nloc, nx); b.st[0] = nloc; b.st[1] = nx; }
;         const unsigned old = xb_add(&bar[XB_XSUB(b.x)], 1u);
;         const unsigned gen = old / nloc;
;         if (old + 1u == (gen + 1u) * nloc) {
;             __builtin_amdgcn_fence(__ATOMIC_RELEASE, "agent");
;             asm volatile("s_waitcnt vmcnt(0)" ::: "memory");
;             const unsigned og = xb_add(&bar[XB_TOP], 1u);
;             const unsigned tg = og / nx;
;             if (og + 1u == (tg + 1u) * nx) xb_add(&bar[XB_TOPGEN], 1u);
;             else XB_SPIN(xb_ld(&bar[XB_TOPGEN]) == tg, bar);
;             __builtin_amdgcn_fence(__ATOMIC_ACQUIRE, "agent");
;             xb_add(&bar[XB_XGEN(b.x)], 1u);
;             asm volatile("s_waitcnt vmcnt(0)" ::: "memory");
;         } else {
;             XB_SPIN(xb_ld(&bar[XB_XGEN(b.x)]) == gen, bar);
;             __builtin_amdgcn_fence(__ATOMIC_ACQUIRE, "agent");
;             asm volatile("s_waitcnt vmcnt(0)" ::: "memory");
;         }
;     }
;     __syncthreads();
; }
.LBB0_150:
	s_waitcnt vmcnt(0)
	s_barrier
	s_mov_b64 s[0:1], exec
	v_readlane_b32 s4, v255, 4
	v_readlane_b32 s5, v255, 5
	s_and_b64 s[4:5], s[0:1], s[4:5]
	s_xor_b64 s[0:1], s[4:5], s[0:1]
	s_mov_b64 exec, s[4:5]
	s_cbranch_execz .LBB0_203
	s_add_i32 s8, 0, 0x20160
	v_mov_b32_e32 v0, s8
	ds_read_b32 v2, v0
	ds_read_b32 v3, v0 offset:4
	v_readlane_b32 s9, v255, 3
	v_mov_b32_e32 v1, 1
	s_lshl_b32 s9, s9, 8
	s_add_i32 s9, s9, 0x8000
	v_mov_b32_e32 v0, s9
	s_waitcnt vmcnt(0) lgkmcnt(0)
	global_atomic_add v4, v0, v1, s[92:93] sc0
	v_readfirstlane_b32 s10, v2
	v_readfirstlane_b32 s11, v3
	s_nop 3
	s_mul_i32 s10, s10, 2
	s_mul_i32 s11, s11, 2
	s_waitcnt vmcnt(0)
	v_readfirstlane_b32 s12, v4
	s_nop 3
	s_add_i32 s12, s12, 1
	s_cmp_lg_u32 s12, s10
	s_cbranch_scc1 .Lmy_gb2_wait
	buffer_wbl2 sc1
	s_waitcnt vmcnt(0) lgkmcnt(0)
	v_mov_b32_e32 v0, 0x9000
	global_atomic_add v0, v1, s[92:93]

; __device__ __forceinline__ unsigned xb_ld(unsigned* p)              { return __hip_atomic_load(p, __ATOMIC_RELAXED, __HIP_MEMORY_SCOPE_AGENT); }
; __device__ __forceinline__ unsigned xb_add(unsigned* p, unsigned v) { return __hip_atomic_fetch_add(p, v, __ATOMIC_RELAXED, __HIP_MEMORY_SCOPE_AGENT); }
; #define XB_SPIN(cond, bar) do { unsigned _sp = 0; while (cond) { __builtin_amdgcn_s_sleep(1); \
;     if ((++_sp & 255u) == 0u) { if (xb_ld(&(bar)[XB_TMO])) break; if (_sp > XB_SPIN_CAP) { atomicAdd(&(bar)[XB_TMO], 1u); break; } } } } while (0)
; __device__ __forceinline__ void xcd_barrier(const XcdBarrier& b) {
;     asm volatile("s_waitcnt vmcnt(0)" ::: "memory");
;     __syncthreads();
;     if (threadIdx.x == 0) {
;         unsigned* bar = b.bar;
;         __builtin_amdgcn_s_waitcnt(0);
;         unsigned nloc = b.st[0], nx = b.st[1];
;         if (nloc == 0u) { xcd_barrier_complete(bar, b.x, nloc, nx); b.st[0] = nloc; b.st[1] = nx; }
;         const unsigned old = xb_add(&bar[XB_XSUB(b.x)], 1u);
;         const unsigned gen = old / nloc;
;         if (old + 1u == (gen + 1u) * nloc) {
;             __builtin_amdgcn_fence(__ATOMIC_RELEASE, "agent");
;             asm volatile("s_waitcnt vmcnt(0)" ::: "memory");
;             const unsigned og = xb_add(&bar[XB_TOP], 1u);
;             const unsigned tg = og / nx;
;             if (og + 1u == (tg + 1u) * nx) xb_add(&bar[XB_TOPGEN], 1u);
;             else XB_SPIN(xb_ld(&bar[XB_TOPGEN]) == tg, bar);
;             __builtin_amdgcn_fence(__ATOMIC_ACQUIRE, "agent");
;             xb_add(&bar[XB_XGEN(b.x)], 1u);
;             asm volatile("s_waitcnt vmcnt(0)" ::: "memory");
;         } else {
;             XB_SPIN(xb_ld(&bar[XB_XGEN(b.x)]) == gen, bar);
;             __builtin_amdgcn_fence(__ATOMIC_ACQUIRE, "agent");
;             asm volatile("s_waitcnt vmcnt(0)" ::: "memory");
;         }
;     }
;     __syncthreads();
; }
.LBB0_549:
	s_waitcnt vmcnt(0)
	s_waitcnt vmcnt(0)
	s_barrier
	s_mov_b64 s[0:1], exec
	v_readlane_b32 s4, v255, 4
	v_readlane_b32 s5, v255, 5
	s_and_b64 s[4:5], s[0:1], s[4:5]
	s_xor_b64 s[0:1], s[4:5], s[0:1]
	s_mov_b64 exec, s[4:5]
	s_cbranch_execz .LBB0_602
	s_add_i32 s8, 0, 0x20160
	v_mov_b32_e32 v0, s8
	ds_read_b32 v2, v0
	ds_read_b32 v3, v0 offset:4
	v_readlane_b32 s9, v255, 3
	v_mov_b32_e32 v1, 1
	s_lshl_b32 s9, s9, 8
	s_add_i32 s9, s9, 0x8000
	v_mov_b32_e32 v0, s9
	s_waitcnt vmcnt(0) lgkmcnt(0)
	global_atomic_add v4, v0, v1, s[92:93] sc0
	v_readfirstlane_b32 s10, v2
	v_readfirstlane_b32 s11, v3
	s_nop 3
	s_mul_i32 s10, s10, 3
	s_mul_i32 s11, s11, 3
	s_waitcnt vmcnt(0)
	v_readfirstlane_b32 s12, v4
	s_nop 3
	s_add_i32 s12, s12, 1
	s_cmp_lg_u32 s12, s10
	s_cbranch_scc1 .Lmy_gb3_wait
	buffer_wbl2 sc1
	s_waitcnt vmcnt(0) lgkmcnt(0)
	v_mov_b32_e32 v0, 0x9000
	global_atomic_add v0, v1, s[92:93]

; __device__ __forceinline__ unsigned xb_ld(unsigned* p)              { return __hip_atomic_load(p, __ATOMIC_RELAXED, __HIP_MEMORY_SCOPE_AGENT); }
; __device__ __forceinline__ unsigned xb_add(unsigned* p, unsigned v) { return __hip_atomic_fetch_add(p, v, __ATOMIC_RELAXED, __HIP_MEMORY_SCOPE_AGENT); }
; #define XB_SPIN(cond, bar) do { unsigned _sp = 0; while (cond) { __builtin_amdgcn_s_sleep(1); \
;     if ((++_sp & 255u) == 0u) { if (xb_ld(&(bar)[XB_TMO])) break; if (_sp > XB_SPIN_CAP) { atomicAdd(&(bar)[XB_TMO], 1u); break; } } } } while (0)
; __device__ __forceinline__ void xcd_barrier(const XcdBarrier& b) {
;     asm volatile("s_waitcnt vmcnt(0)" ::: "memory");
;     __syncthreads();
;     if (threadIdx.x == 0) {
;         unsigned* bar = b.bar;
;         __builtin_amdgcn_s_waitcnt(0);
;         unsigned nloc = b.st[0], nx = b.st[1];
;         if (nloc == 0u) { xcd_barrier_complete(bar, b.x, nloc, nx); b.st[0] = nloc; b.st[1] = nx; }
;         const unsigned old = xb_add(&bar[XB_XSUB(b.x)], 1u);
;         const unsigned gen = old / nloc;
;         if (old + 1u == (gen + 1u) * nloc) {
;             __builtin_amdgcn_fence(__ATOMIC_RELEASE, "agent");
;             asm volatile("s_waitcnt vmcnt(0)" ::: "memory");
;             const unsigned og = xb_add(&bar[XB_TOP], 1u);
;             const unsigned tg = og / nx;
;             if (og + 1u == (tg + 1u) * nx) xb_add(&bar[XB_TOPGEN], 1u);
;             else XB_SPIN(xb_ld(&bar[XB_TOPGEN]) == tg, bar);
;             __builtin_amdgcn_fence(__ATOMIC_ACQUIRE, "agent");
;             xb_add(&bar[XB_XGEN(b.x)], 1u);
;             asm volatile("s_waitcnt vmcnt(0)" ::: "memory");
;         } else {
;             XB_SPIN(xb_ld(&bar[XB_XGEN(b.x)]) == gen, bar);
;             __builtin_amdgcn_fence(__ATOMIC_ACQUIRE, "agent");
;             asm volatile("s_waitcnt vmcnt(0)" ::: "memory");
;         }
;     }
;     __syncthreads();
; }
.LBB0_908:
	s_waitcnt vmcnt(0)
	s_waitcnt vmcnt(0)
	s_barrier
	s_mov_b64 s[0:1], exec
	v_readlane_b32 s6, v255, 4
	v_readlane_b32 s7, v255, 5
	s_and_b64 s[6:7], s[0:1], s[6:7]
	s_xor_b64 s[0:1], s[6:7], s[0:1]
	s_mov_b64 exec, s[6:7]
	s_cbranch_execz .LBB0_961
	s_add_i32 s8, 0, 0x20160
	v_mov_b32_e32 v0, s8
	ds_read_b32 v2, v0
	ds_read_b32 v3, v0 offset:4
	v_readlane_b32 s9, v255, 3
	v_mov_b32_e32 v1, 1
	s_lshl_b32 s9, s9, 8
	s_add_i32 s9, s9, 0x8000
	v_mov_b32_e32 v0, s9
	s_waitcnt vmcnt(0) lgkmcnt(0)
	global_atomic_add v4, v0, v1, s[92:93] sc0
	v_readfirstlane_b32 s10, v2
	v_readfirstlane_b32 s11, v3
	s_nop 3
	s_mul_i32 s10, s10, 4
	s_mul_i32 s11, s11, 4
	s_waitcnt vmcnt(0)
	v_readfirstlane_b32 s12, v4
	s_nop 3
	s_add_i32 s12, s12, 1
	s_cmp_lg_u32 s12, s10
	s_cbranch_scc1 .Lmy_gb4_wait
	buffer_wbl2 sc1
	s_waitcnt vmcnt(0) lgkmcnt(0)
	v_mov_b32_e32 v0, 0x9000
	global_atomic_add v0, v1, s[92:93]

; __device__ __forceinline__ unsigned xb_ld(unsigned* p)              { return __hip_atomic_load(p, __ATOMIC_RELAXED, __HIP_MEMORY_SCOPE_AGENT); }
; __device__ __forceinline__ unsigned xb_add(unsigned* p, unsigned v) { return __hip_atomic_fetch_add(p, v, __ATOMIC_RELAXED, __HIP_MEMORY_SCOPE_AGENT); }
; #define XB_SPIN(cond, bar) do { unsigned _sp = 0; while (cond) { __builtin_amdgcn_s_sleep(1); \
;     if ((++_sp & 255u) == 0u) { if (xb_ld(&(bar)[XB_TMO])) break; if (_sp > XB_SPIN_CAP) { atomicAdd(&(bar)[XB_TMO], 1u); break; } } } } while (0)
; __device__ __forceinline__ void xcd_barrier(const XcdBarrier& b) {
;     asm volatile("s_waitcnt vmcnt(0)" ::: "memory");
;     __syncthreads();
;     if (threadIdx.x == 0) {
;         unsigned* bar = b.bar;
;         __builtin_amdgcn_s_waitcnt(0);
;         unsigned nloc = b.st[0], nx = b.st[1];
;         if (nloc == 0u) { xcd_barrier_complete(bar, b.x, nloc, nx); b.st[0] = nloc; b.st[1] = nx; }
;         const unsigned old = xb_add(&bar[XB_XSUB(b.x)], 1u);
;         const unsigned gen = old / nloc;
;         if (old + 1u == (gen + 1u) * nloc) {
;             __builtin_amdgcn_fence(__ATOMIC_RELEASE, "agent");
;             asm volatile("s_waitcnt vmcnt(0)" ::: "memory");
;             const unsigned og = xb_add(&bar[XB_TOP], 1u);
;             const unsigned tg = og / nx;
;             if (og + 1u == (tg + 1u) * nx) xb_add(&bar[XB_TOPGEN], 1u);
;             else XB_SPIN(xb_ld(&bar[XB_TOPGEN]) == tg, bar);
;             __builtin_amdgcn_fence(__ATOMIC_ACQUIRE, "agent");
;             xb_add(&bar[XB_XGEN(b.x)], 1u);
;             asm volatile("s_waitcnt vmcnt(0)" ::: "memory");
;         } else {
;             XB_SPIN(xb_ld(&bar[XB_XGEN(b.x)]) == gen, bar);
;             __builtin_amdgcn_fence(__ATOMIC_ACQUIRE, "agent");
;             asm volatile("s_waitcnt vmcnt(0)" ::: "memory");
;         }
;     }
;     __syncthreads();
; }
.LBB0_981:
	s_waitcnt vmcnt(0)
	s_barrier
	s_mov_b64 s[0:1], exec
	v_readlane_b32 s4, v255, 4
	v_readlane_b32 s5, v255, 5
	s_and_b64 s[4:5], s[0:1], s[4:5]
	s_xor_b64 s[0:1], s[4:5], s[0:1]
	s_mov_b64 exec, s[4:5]
	s_cbranch_execz .LBB0_1034
	s_add_i32 s8, 0, 0x20160
	v_mov_b32_e32 v0, s8
	ds_read_b32 v2, v0
	ds_read_b32 v3, v0 offset:4
	v_readlane_b32 s9, v255, 3
	v_mov_b32_e32 v1, 1
	s_lshl_b32 s9, s9, 8
	s_add_i32 s9, s9, 0x8000
	v_mov_b32_e32 v0, s9
	s_waitcnt vmcnt(0) lgkmcnt(0)
	global_atomic_add v4, v0, v1, s[92:93] sc0
	v_readfirstlane_b32 s10, v2
	v_readfirstlane_b32 s11, v3
	s_nop 3
	s_mul_i32 s10, s10, 5
	s_mul_i32 s11, s11, 5
	s_waitcnt vmcnt(0)
	v_readfirstlane_b32 s12, v4
	s_nop 3
	s_add_i32 s12, s12, 1
	s_cmp_lg_u32 s12, s10
	s_cbranch_scc1 .Lmy_gb5_wait
	buffer_wbl2 sc1
	s_waitcnt vmcnt(0) lgkmcnt(0)
	v_mov_b32_e32 v0, 0x9000
	global_atomic_add v0, v1, s[92:93]
